# scan per-unit prefetch split over two waves: wave 0 keeps the next unit's first tiles, wave 4 touches P5's o|z rows keyed by the unit being finished
# speedup vs baseline: 1.0053x; 1.0053x over previous
.Lpf_a:
	v_readfirstlane_b32 s26, v184
	s_cmp_lt_u32 s26, 64
	s_cbranch_scc1 .Lpf_a_w0
	s_lshr_b32 s26, s26, 6
	s_cmp_eq_u32 s26, 4
	s_cbranch_scc0 .Lpf_a_end
	s_and_b32 s58, s66, 0x1ff
	s_add_u32 s58, s58, 0x200
	s_mul_i32 s58, s58, 0x18000
	s_add_u32 s26, s28, 0x8501000
	s_addc_u32 s27, s29, 0
	s_add_u32 s26, s26, s58
	s_addc_u32 s27, s27, 0
	v_mbcnt_hi_u32_b32 v47, -1, v185
	v_lshlrev_b32_e32 v47, 6, v47
	global_load_dword v44, v47, s[26:27]
	s_add_u32 s26, s26, 0x3000
	s_addc_u32 s27, s27, 0
	global_load_dword v44, v47, s[26:27]
	s_add_u32 s26, s26, 0x3000
	s_addc_u32 s27, s27, 0
	global_load_dword v44, v47, s[26:27]
	s_add_u32 s26, s26, 0x3000
	s_addc_u32 s27, s27, 0
	global_load_dword v44, v47, s[26:27]
	s_add_u32 s26, s26, 0x3000
	s_addc_u32 s27, s27, 0
	global_load_dword v44, v47, s[26:27]
	s_add_u32 s26, s26, 0x3000
	s_addc_u32 s27, s27, 0
	global_load_dword v44, v47, s[26:27]
	s_add_u32 s26, s26, 0x3000
	s_addc_u32 s27, s27, 0
	global_load_dword v44, v47, s[26:27]
	s_add_u32 s26, s26, 0x3000
	s_addc_u32 s27, s27, 0
	global_load_dword v44, v47, s[26:27]
	s_branch .Lpf_a_end
.Lpf_a_w0:
	v_readfirstlane_b32 s27, v255
	s_cmp_ge_u32 s27, 0x400
	s_cbranch_scc1 .Lpf_a_end
	s_and_b32 s58, s27, 0x1ff
	s_lshr_b32 s59, s58, 4
	s_lshl_b32 s59, s59, 7
	s_cmp_lt_u32 s27, 0x200
	s_cbranch_scc0 .Lpf_a_ssd
	s_mul_i32 s60, s59, 0x3000
	s_bfe_u32 s61, s58, 0x20002
	s_lshl_b32 s61, s61, 8
	s_and_b32 s72, s58, 3
	s_lshl_b32 s72, s72, 7
	s_lshl_b32 s73, s61, 1
	s_add_u32 s72, s72, s73
	s_add_u32 s72, s72, 0x800
	s_add_u32 s73, s61, 0x400
	s_movk_i32 s98, 0x3000
	s_mov_b32 s99, 0x8500000
	s_branch .Lpf_a_go

.Lpf_b:
	v_readfirstlane_b32 s26, v184
	s_cmp_lt_u32 s26, 64
	s_cbranch_scc1 .Lpf_b_w0
	s_lshr_b32 s26, s26, 6
	s_cmp_eq_u32 s26, 4
	s_cbranch_scc0 .Lpf_b_end
	s_and_b32 s58, s66, 0x1ff
	s_mul_i32 s58, s58, 0x18000
	s_add_u32 s26, s28, 0x8501000
	s_addc_u32 s27, s29, 0
	s_add_u32 s26, s26, s58
	s_addc_u32 s27, s27, 0
	v_mbcnt_hi_u32_b32 v47, -1, v185
	v_lshlrev_b32_e32 v47, 6, v47
	global_load_dword v44, v47, s[26:27]
	s_add_u32 s26, s26, 0x3000
	s_addc_u32 s27, s27, 0
	global_load_dword v44, v47, s[26:27]
	s_add_u32 s26, s26, 0x3000
	s_addc_u32 s27, s27, 0
	global_load_dword v44, v47, s[26:27]
	s_add_u32 s26, s26, 0x3000
	s_addc_u32 s27, s27, 0
	global_load_dword v44, v47, s[26:27]
	s_add_u32 s26, s26, 0x3000
	s_addc_u32 s27, s27, 0
	global_load_dword v44, v47, s[26:27]
	s_add_u32 s26, s26, 0x3000
	s_addc_u32 s27, s27, 0
	global_load_dword v44, v47, s[26:27]
	s_add_u32 s26, s26, 0x3000
	s_addc_u32 s27, s27, 0
	global_load_dword v44, v47, s[26:27]
	s_add_u32 s26, s26, 0x3000
	s_addc_u32 s27, s27, 0
	global_load_dword v44, v47, s[26:27]
	s_branch .Lpf_b_end

.Lpf_b_end:
	s_branch .LBB0_631
	s_nop 0
	s_nop 0
	s_nop 0
	s_nop 0
	s_nop 0
	s_nop 0
	s_nop 0
	s_nop 0
	s_nop 0
	s_nop 0
	s_nop 0
	s_nop 0
	s_nop 0
	s_nop 0
	s_nop 0
	s_nop 0
	s_nop 0
	s_nop 0
	s_nop 0
	s_nop 0
	s_nop 0
	s_nop 0
	s_nop 0
	s_nop 0
	s_nop 0
	s_nop 0
	s_nop 0
	s_nop 0
	s_nop 0
	s_nop 0
	s_nop 0
	s_nop 0
	s_nop 0
	s_nop 0
	s_nop 0
	s_nop 0
	s_nop 0
	s_nop 0
	s_nop 0
	s_nop 0
	s_nop 0
	s_nop 0
	s_nop 0
	s_nop 0
	s_nop 0
	s_nop 0
	s_nop 0
	s_nop 0
	s_nop 0
	s_nop 0
	s_nop 0
	s_nop 0
	s_nop 0
	s_nop 0
	s_nop 0
	s_nop 0
	s_nop 0
	s_nop 0
	s_nop 0
	s_nop 0
	s_nop 0
	s_nop 0
	s_nop 0
	s_nop 0
	s_nop 0
	s_nop 0
	s_nop 0
	s_nop 0
	s_nop 0
	s_nop 0
	s_nop 0
	s_nop 0
	s_nop 0
	s_nop 0
	s_nop 0
	s_nop 0
	s_nop 0
	s_nop 0
	s_nop 0
	s_nop 0
	s_nop 0
	s_nop 0
	s_nop 0
	s_nop 0
	s_nop 0
	s_nop 0
	s_nop 0
	s_nop 0
	s_nop 0
	s_nop 0
	s_nop 0
	s_nop 0
	s_nop 0
	s_nop 0
	s_nop 0
	s_nop 0
	s_nop 0
	s_nop 0
	s_nop 0
	s_nop 0
	s_nop 0
	s_nop 0
	s_nop 0
	s_nop 0
	s_nop 0
	s_nop 0
	s_nop 0
	s_nop 0
	s_nop 0
	s_nop 0
	s_nop 0
	s_nop 0
	s_nop 0
	s_nop 0
	s_nop 0
	s_nop 0
	s_nop 0
	s_nop 0
	s_nop 0
	s_nop 0
	s_nop 0
	s_nop 0
	s_nop 0
	s_nop 0
	s_nop 0
	s_nop 0
	s_nop 0
	s_nop 0
	s_nop 0
	s_nop 0
	s_nop 0
	s_nop 0
	s_nop 0
	s_nop 0
	s_nop 0
	s_nop 0
	s_nop 0
	s_nop 0
	s_nop 0
	s_nop 0
	s_nop 0
	s_nop 0
	s_nop 0
	s_nop 0
	s_nop 0
	s_nop 0
	s_nop 0
	s_nop 0
	s_nop 0
	s_nop 0
	s_nop 0
	s_nop 0
	s_nop 0
	s_nop 0
	s_nop 0
	s_nop 0
	s_nop 0
	s_nop 0
	s_nop 0
	s_nop 0
	s_nop 0
	s_nop 0
	s_nop 0
	s_nop 0
	s_nop 0
	s_nop 0
	s_nop 0
	s_nop 0
	s_nop 0
	s_nop 0
	s_nop 0
	s_nop 0
	s_nop 0
	s_nop 0
	s_nop 0
	s_nop 0
	s_nop 0
	s_nop 0
	s_nop 0
	s_nop 0
	s_nop 0
	s_nop 0
	s_nop 0
	s_nop 0
	s_nop 0
	s_nop 0
	s_nop 0
	s_nop 0
	s_nop 0
	s_nop 0
	s_nop 0
	s_nop 0
	s_nop 0
	s_nop 0
	s_nop 0
	s_nop 0
	s_nop 0
	s_nop 0
	s_nop 0
	s_nop 0
	s_nop 0
	s_nop 0
	s_nop 0
	s_nop 0
	s_nop 0
	s_nop 0
	s_nop 0
	s_nop 0
	s_nop 0
	s_nop 0
	s_nop 0
	s_nop 0
	s_nop 0
	s_nop 0
	s_nop 0
	s_nop 0
	s_nop 0
	s_nop 0
	s_nop 0
	s_nop 0
	s_nop 0
	s_nop 0
	s_nop 0
	s_nop 0
	s_nop 0
	s_nop 0
	s_nop 0
	s_nop 0
	s_nop 0
	s_nop 0
	s_nop 0
	s_nop 0
	s_nop 0
	s_nop 0
	s_nop 0
	s_nop 0
	s_nop 0
	s_nop 0
	s_nop 0
	s_nop 0
	s_nop 0
	s_nop 0
	s_nop 0
	s_nop 0
	s_nop 0
	s_nop 0
	s_nop 0
	s_nop 0
	s_nop 0
	s_nop 0
	s_nop 0
	s_nop 0
	s_nop 0
	s_nop 0
	s_nop 0
	s_nop 0
	s_nop 0
	s_nop 0
	s_nop 0
	s_nop 0
	s_nop 0
	s_nop 0
	s_nop 0
	s_nop 0
	s_nop 0
	s_nop 0
	s_nop 0
	s_nop 0
	s_nop 0
	s_nop 0
	s_nop 0
	s_nop 0
	s_nop 0
	s_nop 0
	s_nop 0
	s_nop 0
	s_nop 0
	s_nop 0
	s_nop 0
	s_nop 0
	s_nop 0
	s_nop 0
	s_nop 0
	s_nop 0
	s_nop 0
	s_nop 0
	s_nop 0
	s_nop 0
	s_nop 0
	s_nop 0
	s_nop 0
	s_nop 0
	s_nop 0
	s_nop 0
	s_nop 0
	s_nop 0
	s_nop 0
	s_nop 0
	s_nop 0
	s_nop 0
	s_nop 0
	s_nop 0
	s_nop 0
	s_nop 0
	s_nop 0
	s_nop 0
	s_nop 0
	s_nop 0
	s_nop 0
	s_nop 0
	s_nop 0
	s_nop 0
	s_nop 0
	s_nop 0
	s_nop 0
	s_nop 0
	s_nop 0
	s_nop 0
	s_nop 0
	s_nop 0
	s_nop 0
	s_nop 0
	s_nop 0
	s_nop 0
	s_nop 0
	s_nop 0
	s_nop 0
	s_nop 0
	s_nop 0
	s_nop 0
	s_nop 0
	s_nop 0
	s_nop 0
	s_nop 0
	s_nop 0
	s_nop 0
	s_nop 0
	s_nop 0
	s_nop 0
	s_nop 0
	s_nop 0
	s_nop 0
	s_nop 0
	s_nop 0
	s_nop 0
	s_nop 0
	s_nop 0
	s_nop 0
	s_nop 0
	s_nop 0
	s_nop 0
	s_nop 0
	s_nop 0
	s_nop 0
	s_nop 0
	s_nop 0
	s_nop 0
	s_nop 0
	s_nop 0
	s_nop 0
	s_nop 0
	s_nop 0
	s_nop 0
	s_nop 0
	s_nop 0
	s_nop 0
	s_nop 0
	s_nop 0
	s_nop 0
	s_nop 0
	s_nop 0
	s_nop 0
	s_nop 0
	s_nop 0
	s_nop 0
	s_nop 0
	s_nop 0
	s_nop 0
	s_nop 0
	s_nop 0
	s_nop 0
	s_nop 0
	s_nop 0
	s_nop 0
	s_nop 0
	s_nop 0
	s_nop 0
	s_nop 0
	s_nop 0
	s_nop 0
	s_nop 0
	s_nop 0
	s_nop 0
	s_nop 0
	s_nop 0
	s_nop 0
	s_nop 0
	s_nop 0
	s_nop 0
	s_nop 0
	s_nop 0
	s_nop 0
	s_nop 0
	s_nop 0
	s_nop 0
	s_nop 0
	s_nop 0
	s_nop 0
	s_nop 0
	s_nop 0
	s_nop 0
	s_nop 0
	s_nop 0
	s_nop 0
	s_nop 0
	s_nop 0
	s_nop 0
	s_nop 0
	s_nop 0
	s_nop 0
	s_nop 0
	s_nop 0
	s_nop 0
	s_nop 0
	s_nop 0
	s_nop 0
	s_nop 0
	s_nop 0
	s_nop 0
	s_nop 0
	s_nop 0
	s_nop 0
	s_nop 0
	s_nop 0
	s_nop 0
	s_nop 0
	s_nop 0
	s_nop 0
	s_nop 0
	s_nop 0
	s_nop 0
	s_nop 0
	s_nop 0
	s_nop 0
	s_nop 0
	s_nop 0
	s_nop 0
	s_nop 0
	s_nop 0
	s_nop 0
	s_nop 0
	s_nop 0
	s_nop 0
	s_nop 0
	s_nop 0
	s_nop 0
	s_nop 0
	s_nop 0
	s_nop 0
	s_nop 0
	s_nop 0
	s_nop 0
	s_nop 0
	s_nop 0
	s_nop 0
	s_nop 0
	s_nop 0
	s_nop 0
	s_nop 0
	s_nop 0
	s_nop 0
	s_nop 0
	s_nop 0
	s_nop 0
	s_nop 0
	s_nop 0
	s_nop 0
	s_nop 0
	s_nop 0
	s_nop 0
	s_nop 0
	s_nop 0
	s_nop 0
	s_nop 0
	s_nop 0
	s_nop 0
	s_nop 0
	s_nop 0
	s_nop 0
	s_nop 0
	s_nop 0
	s_nop 0
	s_nop 0
	s_nop 0
	s_nop 0
	s_nop 0
	s_nop 0
	s_nop 0
	s_nop 0
	s_nop 0
	s_nop 0
	s_nop 0
	s_nop 0
	s_nop 0
	s_nop 0
	s_nop 0
	s_nop 0
	s_nop 0
	s_nop 0
	s_nop 0
	s_nop 0
	s_nop 0
	s_nop 0
	s_nop 0
	s_nop 0
	s_nop 0
	s_nop 0
	s_nop 0
	s_nop 0
	s_nop 0
	s_nop 0
	s_nop 0
	s_nop 0
	s_nop 0
	s_nop 0
	s_nop 0
	s_nop 0
	s_nop 0
	s_nop 0
	s_nop 0
	s_nop 0
	s_nop 0
	s_nop 0
	s_nop 0
	s_nop 0
	s_nop 0
	s_nop 0
	s_nop 0
	s_nop 0
	s_nop 0
	s_nop 0
	s_nop 0
	s_nop 0
	s_nop 0
	s_nop 0
	s_nop 0
	s_nop 0
	s_nop 0
	s_nop 0
	s_nop 0
	s_nop 0
	s_nop 0
	s_nop 0
	s_nop 0
	s_nop 0
	s_nop 0
	s_nop 0
	s_nop 0
	s_nop 0
	s_nop 0
	s_nop 0
	s_nop 0
	s_nop 0
	s_nop 0
	s_nop 0
	s_nop 0
	s_nop 0
	s_nop 0
	s_nop 0
	s_nop 0
	s_nop 0
	s_nop 0
	s_nop 0
	s_nop 0
	s_nop 0
	s_nop 0
	s_nop 0
	s_nop 0
	s_nop 0
	s_nop 0
	s_nop 0
	s_nop 0
	s_nop 0
	s_nop 0
	s_nop 0
	s_nop 0
	s_nop 0
	s_nop 0
	s_nop 0
	s_nop 0
	s_nop 0
	s_nop 0
	s_nop 0
	s_nop 0
	s_nop 0
	s_nop 0
	s_nop 0
	s_nop 0
	s_nop 0
	s_nop 0
	s_nop 0
	s_nop 0
	s_nop 0
	s_nop 0
	s_nop 0
	s_nop 0
	s_nop 0
	s_nop 0
	s_nop 0
	s_nop 0
	s_nop 0
	s_nop 0
	s_nop 0
	s_nop 0
	s_nop 0
	s_nop 0
	s_nop 0
	s_nop 0
	s_nop 0
	s_nop 0
	s_nop 0
	s_nop 0
	s_nop 0
	s_nop 0
	s_nop 0
	s_nop 0
	s_nop 0
	s_nop 0
	s_nop 0
	s_nop 0
	s_nop 0
	s_nop 0
	s_nop 0
	s_nop 0
	s_nop 0
	s_nop 0
	s_nop 0
	s_nop 0
	s_nop 0
	s_nop 0
	s_nop 0
	s_nop 0
	s_nop 0
	s_nop 0
	s_nop 0
	s_nop 0
	s_nop 0
	s_nop 0
	s_nop 0
	s_nop 0
	s_nop 0
	s_nop 0
	s_nop 0
	s_nop 0
	s_nop 0
	s_nop 0
	s_nop 0
	s_nop 0
	s_nop 0
	s_nop 0
	s_nop 0
	s_nop 0
	s_nop 0
	s_nop 0
	s_nop 0
	s_nop 0
	s_nop 0
	s_nop 0
	s_nop 0
	s_nop 0
	s_nop 0
	s_nop 0
	s_nop 0
	s_nop 0
	s_nop 0
	s_nop 0
	s_nop 0
	s_nop 0
	s_nop 0
	s_nop 0
	s_nop 0
	s_nop 0
	s_nop 0
	s_nop 0
	s_nop 0
	s_nop 0
	s_nop 0
	s_nop 0
	s_nop 0
	s_nop 0
	s_nop 0
	s_nop 0
	s_nop 0
	s_nop 0
	s_nop 0
	s_nop 0
	s_nop 0
	s_nop 0
	s_nop 0
	s_nop 0
	s_nop 0
	s_nop 0
	s_nop 0
	s_nop 0
	s_nop 0
	s_nop 0
	s_nop 0
	s_nop 0
	s_nop 0
	s_nop 0
	s_nop 0
	s_nop 0
	s_nop 0
	s_nop 0
	s_nop 0
	s_nop 0
	s_nop 0
	s_nop 0
	s_nop 0
	s_nop 0
	s_nop 0
	s_nop 0
	s_nop 0
	s_nop 0
	s_nop 0
	s_nop 0
	s_nop 0
	s_nop 0
	s_nop 0
	s_nop 0
	s_nop 0
	s_nop 0
	s_nop 0
	s_nop 0
	s_nop 0
	s_nop 0
	s_nop 0
	s_nop 0
	s_nop 0
	s_nop 0
	s_nop 0
	s_nop 0
	s_nop 0
	s_nop 0
	s_nop 0
	s_nop 0
	s_nop 0
	s_nop 0
	s_nop 0
	s_nop 0
	s_nop 0
	s_nop 0
	s_nop 0
	s_nop 0
	s_nop 0
	s_nop 0
	s_nop 0
	s_nop 0
	s_nop 0
	s_nop 0
	s_nop 0
	s_nop 0
	s_nop 0
	s_nop 0
	s_nop 0
	s_nop 0
	s_nop 0
	s_nop 0
	s_nop 0
	s_nop 0
	s_nop 0
	s_nop 0
	s_nop 0
	s_nop 0
	s_nop 0
	s_nop 0
	s_nop 0
	s_nop 0
	s_nop 0
	s_nop 0
	s_nop 0
	s_nop 0
	s_nop 0
	s_nop 0
	s_nop 0
	s_nop 0
	s_nop 0
	s_nop 0
	s_nop 0
	s_nop 0
	s_nop 0
	s_nop 0
	s_nop 0
	s_nop 0
	s_nop 0
	s_nop 0
	s_nop 0
	s_nop 0
	s_nop 0
	s_nop 0
	s_nop 0
	s_nop 0
	s_nop 0
	s_nop 0
	s_nop 0
	s_nop 0
	s_nop 0
	s_nop 0
	s_nop 0
	s_nop 0
	s_nop 0
	s_nop 0
	s_nop 0
	s_nop 0
	s_nop 0
	s_nop 0
	s_nop 0
	s_nop 0
	s_nop 0
	s_nop 0
	s_nop 0
	s_nop 0
	s_nop 0
	s_nop 0
	s_nop 0
	s_nop 0
	s_nop 0
	s_nop 0
	s_nop 0
	s_nop 0
	s_nop 0
	s_nop 0
	s_nop 0
	s_nop 0
	s_nop 0
	s_nop 0
	s_nop 0
	s_nop 0
	s_nop 0
	s_nop 0
	s_nop 0
	s_nop 0
	s_nop 0
	s_nop 0
	s_nop 0
	s_nop 0
	s_nop 0
	s_nop 0
	s_nop 0
	s_nop 0
	s_nop 0
	s_nop 0
	s_nop 0
	s_nop 0
	s_nop 0
	s_nop 0
	s_nop 0
	s_nop 0
	s_nop 0
	s_nop 0
	s_nop 0
	s_nop 0
	s_nop 0
	s_nop 0
	s_nop 0
	s_nop 0
	s_nop 0
	s_nop 0
	s_nop 0
	s_nop 0
	s_nop 0
	s_nop 0
	s_nop 0
	s_nop 0
	s_nop 0
	s_nop 0
	s_nop 0
	s_nop 0
	s_nop 0
	s_nop 0
	s_nop 0
	s_nop 0
	s_nop 0
	s_nop 0
	s_nop 0
	s_nop 0
	s_nop 0
	s_nop 0
	s_nop 0
	s_nop 0
	s_nop 0
	s_nop 0
	s_nop 0
	s_nop 0
	s_nop 0
	s_nop 0
	s_nop 0
	s_nop 0
	s_nop 0
	s_nop 0
	s_nop 0
	s_nop 0
	s_nop 0
	s_nop 0
	s_nop 0
	s_nop 0
	s_nop 0
	s_nop 0
	s_nop 0
	s_nop 0
	s_nop 0
	s_nop 0
	s_nop 0
	s_nop 0
	s_nop 0
	s_nop 0
	s_nop 0
	s_nop 0
	s_nop 0
	s_nop 0
	s_nop 0
	s_nop 0
	s_nop 0
	s_nop 0
	s_nop 0
	s_nop 0
	s_nop 0
	s_nop 0
	s_nop 0
	s_nop 0
	s_nop 0
	s_nop 0
	s_nop 0
	s_nop 0
	s_nop 0
	s_nop 0
	s_nop 0
	s_nop 0
	s_nop 0
	s_nop 0
	s_nop 0
	s_nop 0
	s_nop 0
	s_nop 0
	s_nop 0
	s_nop 0
	s_nop 0
	s_nop 0
	s_nop 0
	s_nop 0
	s_nop 0
	s_nop 0
	s_nop 0
	s_nop 0
	s_nop 0
	s_nop 0
	s_nop 0
	s_nop 0
	s_nop 0
	s_nop 0
	s_nop 0
	s_nop 0
	s_nop 0
	s_nop 0
	s_nop 0
	s_nop 0
	s_nop 0
	s_nop 0
	s_nop 0
	s_nop 0
	s_nop 0
	s_nop 0
	s_nop 0
	s_nop 0
	s_nop 0
	s_nop 0
	s_nop 0
	s_nop 0
	s_nop 0
	s_nop 0
	s_nop 0
	s_nop 0
	s_nop 0
	s_nop 0
	s_nop 0
	s_nop 0
	s_nop 0
	s_nop 0
	s_nop 0
	s_nop 0
	s_nop 0
	s_nop 0
	s_nop 0
	s_nop 0
	s_nop 0
	s_nop 0
	s_nop 0
	s_nop 0
	s_nop 0
	s_nop 0
	s_nop 0
	s_nop 0
	s_nop 0
	s_nop 0
	s_nop 0
	s_nop 0
	s_nop 0
	s_nop 0
	s_nop 0
	s_nop 0
	s_nop 0
	s_nop 0
	s_nop 0
	s_nop 0
	s_nop 0
	s_nop 0
	s_nop 0
	s_nop 0
	s_nop 0
	s_nop 0
	s_nop 0
	s_nop 0
	s_nop 0
	s_nop 0
	s_nop 0
	s_nop 0
	s_nop 0
	s_nop 0
	s_nop 0
	s_nop 0
	s_nop 0
	s_nop 0
	s_nop 0
	s_nop 0
	s_nop 0
	s_nop 0
	s_nop 0
	s_nop 0
	s_nop 0
	s_nop 0
	s_nop 0
	s_nop 0
	s_nop 0
	s_nop 0
	s_nop 0
	s_nop 0
	s_nop 0
	s_nop 0
